# plus: row-statistics xor-16/xor-32 shuffles via v_permlane16/32_swap instead of ds_bpermute round trips
# speedup vs baseline: 1.0128x; 1.0050x over previous
.LBB0_401:
	s_mul_i32 s8, s94, 0x6000
	s_add_u32 s64, s14, s8
	s_mul_hi_u32 s8, s94, 0x6000
	s_addc_u32 s65, s13, s8
	v_lshlrev_b32_e32 v222, 2, v239
	v_lshl_add_u64 v[134:135], s[64:65], 0, v[222:223]
	s_mov_b64 s[8:9], 0x4000
	v_lshl_add_u64 v[138:139], v[134:135], 0, s[8:9]
	s_movk_i32 s8, 0x4000
	v_add_co_u32_e32 v134, vcc, s8, v134
	v_and_b32_e32 v212, 64, v244
	s_nop 0
	v_addc_co_u32_e32 v135, vcc, 0, v135, vcc
	global_load_dwordx4 v[150:153], v[134:135], off
	s_nop 0
	global_load_dwordx4 v[134:137], v[138:139], off offset:528
	global_load_dwordx4 v[146:149], v[138:139], off offset:16
	s_nop 0
	global_load_dwordx4 v[138:141], v[138:139], off offset:512
	v_xor_b32_e32 v211, 16, v244
	v_add_u32_e32 v212, 64, v212
	v_cmp_lt_i32_e32 vcc, v211, v212
	v_mul_f32_e32 v213, v29, v29
	v_fmac_f32_e32 v213, v28, v28
	v_cndmask_b32_e32 v211, v244, v211, vcc
	v_lshlrev_b32_e32 v237, 2, v211
	v_mul_f32_e32 v211, v27, v27
	v_fmac_f32_e32 v211, v26, v26
	v_add_f32_e32 v211, v211, v213
	v_mul_f32_e32 v213, v19, v19
	v_mul_f32_e32 v214, v21, v21
	v_fmac_f32_e32 v213, v18, v18
	v_fmac_f32_e32 v214, v20, v20
	v_add_f32_e32 v213, v213, v214
	v_add_f32_e32 v211, v211, v213
	v_mul_f32_e32 v213, v47, v47
	v_mul_f32_e32 v214, v49, v49
	v_fmac_f32_e32 v213, v46, v46
	v_fmac_f32_e32 v214, v48, v48
	v_add_f32_e32 v213, v213, v214
	v_add_f32_e32 v211, v211, v213
	v_mul_f32_e32 v213, v39, v39
	v_mul_f32_e32 v214, v41, v41
	v_fmac_f32_e32 v213, v38, v38
	v_fmac_f32_e32 v214, v40, v40
	v_add_f32_e32 v213, v213, v214
	v_add_f32_e32 v211, v211, v213
	v_mov_b32_e32 v213, v211
	s_nop 1
	v_permlane16_swap_b32_e32 v213, v211
	v_xor_b32_e32 v214, 32, v244
	v_cmp_lt_i32_e32 vcc, v214, v212
	s_lshl_b32 s10, s95, 3
	s_add_i32 s37, s10, 0
	v_cndmask_b32_e32 v212, v244, v214, vcc
	v_lshlrev_b32_e32 v238, 2, v212
	s_waitcnt lgkmcnt(0)
	v_add_f32_e32 v212, v211, v213
	v_mov_b32_e32 v213, v212
	s_nop 1
	v_permlane32_swap_b32_e32 v213, v212
	v_and_b32_e32 v211, 63, v210
	v_cmp_gt_u32_e64 s[8:9], 16, v211
	s_and_saveexec_b64 s[10:11], s[8:9]
	s_cbranch_execz .LBB0_403
	s_lshl_b32 s13, s57, 11
	s_add_i32 s13, s37, s13
	v_lshl_add_u32 v214, v219, 5, s13
	s_waitcnt lgkmcnt(0)
	v_add_f32_e32 v212, v212, v213
	v_mov_b32_e32 v213, v223
	ds_write_b64 v214, v[212:213]
.LBB0_403:
	s_or_b64 exec, exec, s[10:11]
	v_mul_f32_e32 v212, v43, v43
	s_waitcnt lgkmcnt(0)
	v_mul_f32_e32 v213, v45, v45
	v_fmac_f32_e32 v212, v42, v42
	v_fmac_f32_e32 v213, v44, v44
	v_add_f32_e32 v212, v212, v213
	v_mul_f32_e32 v213, v35, v35
	v_mul_f32_e32 v214, v37, v37
	v_fmac_f32_e32 v213, v34, v34
	v_fmac_f32_e32 v214, v36, v36
	v_add_f32_e32 v213, v213, v214
	v_add_f32_e32 v212, v212, v213
	v_mul_f32_e32 v213, v63, v63
	v_mul_f32_e32 v214, v65, v65
	v_fmac_f32_e32 v213, v62, v62
	v_fmac_f32_e32 v214, v64, v64
	v_add_f32_e32 v213, v213, v214
	v_add_f32_e32 v212, v212, v213
	v_mul_f32_e32 v213, v59, v59
	v_mul_f32_e32 v214, v61, v61
	v_fmac_f32_e32 v213, v58, v58
	v_fmac_f32_e32 v214, v60, v60
	v_add_f32_e32 v213, v213, v214
	v_add_f32_e32 v212, v212, v213
	v_mov_b32_e32 v213, v212
	s_nop 1
	v_permlane16_swap_b32_e32 v213, v212
	s_waitcnt lgkmcnt(0)
	v_add_f32_e32 v212, v212, v213
	v_mov_b32_e32 v213, v212
	s_nop 1
	v_permlane32_swap_b32_e32 v213, v212
	s_and_saveexec_b64 s[10:11], s[8:9]
	s_cbranch_execz .LBB0_405
	s_lshl_b32 s13, s57, 11
	s_add_i32 s13, s37, s13
	v_lshl_add_u32 v214, v219, 5, s13
	s_waitcnt lgkmcnt(0)
	v_add_f32_e32 v212, v212, v213
	v_mov_b32_e32 v213, v223
	ds_write_b64 v214, v[212:213] offset:512
.LBB0_405:
	s_or_b64 exec, exec, s[10:11]
	v_mul_f32_e32 v212, v55, v55
	s_waitcnt lgkmcnt(0)
	v_mul_f32_e32 v213, v57, v57
	v_fmac_f32_e32 v212, v54, v54
	v_fmac_f32_e32 v213, v56, v56
	v_add_f32_e32 v212, v212, v213
	v_mul_f32_e32 v213, v51, v51
	v_mul_f32_e32 v214, v53, v53
	v_fmac_f32_e32 v213, v50, v50
	v_fmac_f32_e32 v214, v52, v52
	v_add_f32_e32 v213, v213, v214
	v_add_f32_e32 v212, v212, v213
	v_mul_f32_e32 v213, v87, v87
	v_mul_f32_e32 v214, v89, v89
	v_fmac_f32_e32 v213, v86, v86
	v_fmac_f32_e32 v214, v88, v88
	v_add_f32_e32 v213, v213, v214
	v_add_f32_e32 v212, v212, v213
	v_mul_f32_e32 v213, v83, v83
	v_mul_f32_e32 v214, v85, v85
	v_fmac_f32_e32 v213, v82, v82
	v_fmac_f32_e32 v214, v84, v84
	v_add_f32_e32 v213, v213, v214
	v_add_f32_e32 v212, v212, v213
	v_mov_b32_e32 v213, v212
	s_nop 1
	v_permlane16_swap_b32_e32 v213, v212
	s_waitcnt lgkmcnt(0)
	v_add_f32_e32 v212, v212, v213
	v_mov_b32_e32 v213, v212
	s_nop 1
	v_permlane32_swap_b32_e32 v213, v212
	s_and_saveexec_b64 s[10:11], s[8:9]
	s_cbranch_execz .LBB0_407
	s_lshl_b32 s13, s57, 11
	s_add_i32 s13, s37, s13
	v_lshl_add_u32 v214, v219, 5, s13
	s_waitcnt lgkmcnt(0)
	v_add_f32_e32 v212, v212, v213
	v_mov_b32_e32 v213, v223
	ds_write_b64 v214, v[212:213] offset:1024
.LBB0_407:
	s_or_b64 exec, exec, s[10:11]
	v_mul_f32_e32 v212, v79, v79
	s_waitcnt lgkmcnt(0)
	v_mul_f32_e32 v213, v81, v81
	v_fmac_f32_e32 v212, v78, v78
	v_fmac_f32_e32 v213, v80, v80
	v_add_f32_e32 v212, v212, v213
	v_mul_f32_e32 v213, v71, v71
	v_mul_f32_e32 v214, v73, v73
	v_fmac_f32_e32 v213, v70, v70
	v_fmac_f32_e32 v214, v72, v72
	v_add_f32_e32 v213, v213, v214
	v_add_f32_e32 v212, v212, v213
	v_mul_f32_e32 v213, v103, v103
	v_mul_f32_e32 v214, v105, v105
	v_fmac_f32_e32 v213, v102, v102
	v_fmac_f32_e32 v214, v104, v104
	v_add_f32_e32 v213, v213, v214
	v_add_f32_e32 v212, v212, v213
	v_mul_f32_e32 v213, v99, v99
	v_mul_f32_e32 v214, v101, v101
	v_fmac_f32_e32 v213, v98, v98
	v_fmac_f32_e32 v214, v100, v100
	v_add_f32_e32 v213, v213, v214
	v_add_f32_e32 v212, v212, v213
	v_mov_b32_e32 v213, v212
	s_nop 1
	v_permlane16_swap_b32_e32 v213, v212
	s_waitcnt lgkmcnt(0)
	v_add_f32_e32 v212, v212, v213
	v_mov_b32_e32 v213, v212
	s_nop 1
	v_permlane32_swap_b32_e32 v213, v212
	s_and_saveexec_b64 s[10:11], s[8:9]
	s_cbranch_execz .LBB0_409
	s_lshl_b32 s13, s57, 11
	s_add_i32 s13, s37, s13
	v_lshl_add_u32 v214, v219, 5, s13
	s_waitcnt lgkmcnt(0)
	v_add_f32_e32 v212, v212, v213
	v_mov_b32_e32 v213, v223
	ds_write_b64 v214, v[212:213] offset:1536
.LBB0_409:
	s_or_b64 exec, exec, s[10:11]
	v_mul_f32_e32 v212, v95, v95
	s_waitcnt lgkmcnt(0)
	v_mul_f32_e32 v213, v97, v97
	v_fmac_f32_e32 v212, v94, v94
	v_fmac_f32_e32 v213, v96, v96
	v_add_f32_e32 v212, v212, v213
	v_mul_f32_e32 v213, v91, v91
	v_mul_f32_e32 v214, v93, v93
	v_fmac_f32_e32 v213, v90, v90
	v_fmac_f32_e32 v214, v92, v92
	v_add_f32_e32 v213, v213, v214
	v_add_f32_e32 v212, v212, v213
	v_mul_f32_e32 v213, v127, v127
	v_mul_f32_e32 v214, v129, v129
	v_fmac_f32_e32 v213, v126, v126
	v_fmac_f32_e32 v214, v128, v128
	v_add_f32_e32 v213, v213, v214
	v_add_f32_e32 v212, v212, v213
	v_mul_f32_e32 v213, v119, v119
	v_mul_f32_e32 v214, v121, v121
	v_fmac_f32_e32 v213, v118, v118
	v_fmac_f32_e32 v214, v120, v120
	v_add_f32_e32 v213, v213, v214
	v_add_f32_e32 v212, v212, v213
	v_mov_b32_e32 v213, v212
	s_nop 1
	v_permlane16_swap_b32_e32 v213, v212
	s_waitcnt lgkmcnt(0)
	v_add_f32_e32 v212, v212, v213
	v_mov_b32_e32 v213, v212
	s_nop 1
	v_permlane32_swap_b32_e32 v213, v212
	s_and_saveexec_b64 s[10:11], s[8:9]
	s_cbranch_execz .LBB0_411
	s_lshl_b32 s13, s57, 11
	s_add_i32 s13, s37, s13
	v_lshl_add_u32 v214, v219, 5, s13
	s_waitcnt lgkmcnt(0)
	v_add_f32_e32 v212, v212, v213
	v_mov_b32_e32 v213, v223
	ds_write_b64 v214, v[212:213] offset:4096
.LBB0_411:
	s_or_b64 exec, exec, s[10:11]
	v_mul_f32_e32 v212, v115, v115
	s_waitcnt lgkmcnt(0)
	v_mul_f32_e32 v213, v117, v117
	v_fmac_f32_e32 v212, v114, v114
	v_fmac_f32_e32 v213, v116, v116
	v_add_f32_e32 v212, v212, v213
	v_mul_f32_e32 v213, v107, v107
	v_mul_f32_e32 v214, v109, v109
	v_fmac_f32_e32 v213, v106, v106
	v_fmac_f32_e32 v214, v108, v108
	v_add_f32_e32 v213, v213, v214
	v_add_f32_e32 v212, v212, v213
	v_mul_f32_e32 v213, v123, v123
	v_mul_f32_e32 v214, v125, v125
	v_fmac_f32_e32 v213, v122, v122
	v_fmac_f32_e32 v214, v124, v124
	v_add_f32_e32 v213, v213, v214
	v_add_f32_e32 v212, v212, v213
	v_mul_f32_e32 v213, v111, v111
	v_mul_f32_e32 v214, v113, v113
	v_fmac_f32_e32 v213, v110, v110
	v_fmac_f32_e32 v214, v112, v112
	v_add_f32_e32 v213, v213, v214
	v_add_f32_e32 v212, v212, v213
	v_mov_b32_e32 v213, v212
	s_nop 1
	v_permlane16_swap_b32_e32 v213, v212
	s_waitcnt lgkmcnt(0)
	v_add_f32_e32 v212, v212, v213
	v_mov_b32_e32 v213, v212
	s_nop 1
	v_permlane32_swap_b32_e32 v213, v212
	s_and_saveexec_b64 s[10:11], s[8:9]
	s_cbranch_execz .LBB0_413
	s_lshl_b32 s13, s57, 11
	s_add_i32 s13, s37, s13
	v_lshl_add_u32 v214, v219, 5, s13
	s_waitcnt lgkmcnt(0)
	v_add_f32_e32 v212, v212, v213
	v_mov_b32_e32 v213, v223
	ds_write_b64 v214, v[212:213] offset:4608
.LBB0_413:
	s_or_b64 exec, exec, s[10:11]
	v_mul_f32_e32 v212, v75, v75
	s_waitcnt lgkmcnt(0)
	v_mul_f32_e32 v213, v77, v77
	v_fmac_f32_e32 v212, v74, v74
	v_fmac_f32_e32 v213, v76, v76
	v_add_f32_e32 v212, v212, v213
	v_mul_f32_e32 v213, v67, v67
	v_mul_f32_e32 v214, v69, v69
	v_fmac_f32_e32 v213, v66, v66
	v_fmac_f32_e32 v214, v68, v68
	v_add_f32_e32 v213, v213, v214
	v_add_f32_e32 v212, v212, v213
	v_mul_f32_e32 v213, v31, v31
	v_mul_f32_e32 v214, v33, v33
	v_fmac_f32_e32 v213, v30, v30
	v_fmac_f32_e32 v214, v32, v32
	v_add_f32_e32 v213, v213, v214
	v_add_f32_e32 v212, v212, v213
	v_mul_f32_e32 v213, v23, v23
	v_mul_f32_e32 v214, v25, v25
	v_fmac_f32_e32 v213, v22, v22
	v_fmac_f32_e32 v214, v24, v24
	v_add_f32_e32 v213, v213, v214
	v_add_f32_e32 v212, v212, v213
	v_mov_b32_e32 v213, v212
	s_nop 1
	v_permlane16_swap_b32_e32 v213, v212
	s_waitcnt lgkmcnt(0)
	v_add_f32_e32 v212, v212, v213
	v_mov_b32_e32 v213, v212
	s_nop 1
	v_permlane32_swap_b32_e32 v213, v212
	s_and_saveexec_b64 s[10:11], s[8:9]
	s_cbranch_execz .LBB0_415
	s_lshl_b32 s13, s57, 11
	s_add_i32 s13, s37, s13
	v_lshl_add_u32 v214, v219, 5, s13
	s_waitcnt lgkmcnt(0)
	v_add_f32_e32 v212, v212, v213
	v_mov_b32_e32 v213, v223
	ds_write_b64 v214, v[212:213] offset:5120
.LBB0_415:
	s_or_b64 exec, exec, s[10:11]
	v_mul_f32_e32 v212, v15, v15
	s_waitcnt lgkmcnt(0)
	v_mul_f32_e32 v213, v17, v17
	v_fmac_f32_e32 v212, v14, v14
	v_fmac_f32_e32 v213, v16, v16
	v_add_f32_e32 v212, v212, v213
	v_mul_f32_e32 v213, v11, v11
	v_mul_f32_e32 v214, v13, v13
	v_fmac_f32_e32 v213, v10, v10
	v_fmac_f32_e32 v214, v12, v12
	v_add_f32_e32 v213, v213, v214
	v_add_f32_e32 v212, v212, v213
	v_mul_f32_e32 v213, v7, v7
	v_mul_f32_e32 v214, v9, v9
	v_fmac_f32_e32 v213, v6, v6
	v_fmac_f32_e32 v214, v8, v8
	v_add_f32_e32 v213, v213, v214
	v_add_f32_e32 v212, v212, v213
	v_mul_f32_e32 v213, v3, v3
	v_mul_f32_e32 v214, v5, v5
	v_fmac_f32_e32 v213, v2, v2
	v_fmac_f32_e32 v214, v4, v4
	v_add_f32_e32 v213, v213, v214
	v_add_f32_e32 v212, v212, v213
	v_mov_b32_e32 v213, v212
	s_nop 1
	v_permlane16_swap_b32_e32 v213, v212
	s_waitcnt lgkmcnt(0)
	v_add_f32_e32 v212, v212, v213
	v_mov_b32_e32 v213, v212
	s_nop 1
	v_permlane32_swap_b32_e32 v213, v212
	s_and_saveexec_b64 s[10:11], s[8:9]
	s_cbranch_execz .LBB0_417
	s_lshl_b32 s13, s57, 11
	s_add_i32 s13, s37, s13
	v_lshl_add_u32 v214, v219, 5, s13
	s_waitcnt lgkmcnt(0)
	v_add_f32_e32 v212, v212, v213
	v_mov_b32_e32 v213, v223
	ds_write_b64 v214, v[212:213] offset:5632

.LBB0_545:
	s_and_b64 vcc, exec, s[6:7]
	s_cbranch_vccnz .LBB0_357
	v_lshl_add_u64 v[130:131], s[64:65], 0, v[222:223]
	v_add_co_u32_e32 v132, vcc, 0x6000, v130
	s_mov_b64 s[6:7], 0x6000
	s_nop 0
	v_addc_co_u32_e32 v133, vcc, 0, v131, vcc
	v_lshl_add_u64 v[134:135], v[130:131], 0, s[6:7]
	global_load_dwordx4 v[138:141], v[132:133], off
	global_load_dwordx4 v[146:149], v[134:135], off offset:16
	s_mov_b64 s[6:7], 0x8000
	v_lshl_add_u64 v[154:155], v[130:131], 0, s[6:7]
	v_add_co_u32_e32 v130, vcc, 0x8000, v130
	s_waitcnt vmcnt(1)
	v_pk_mul_f32 v[164:165], v[28:29], v[140:141]
	v_addc_co_u32_e32 v131, vcc, 0, v131, vcc
	global_load_dwordx4 v[158:161], v[130:131], off
	global_load_dwordx4 v[150:153], v[154:155], off offset:16
	s_nop 0
	global_load_dwordx4 v[130:133], v[134:135], off offset:528
	s_nop 0
	global_load_dwordx4 v[134:137], v[134:135], off offset:512
	s_nop 0
	global_load_dwordx4 v[142:145], v[154:155], off offset:528
	s_nop 0
	global_load_dwordx4 v[154:157], v[154:155], off offset:512
	v_pk_mul_f32 v[166:167], v[26:27], v[138:139]
	v_max_f32_e64 v164, |v164|, |v165|
	v_max_f32_e64 v166, |v166|, |v167|
	v_max3_f32 v168, v166, 0, v164
	s_waitcnt vmcnt(6)
	v_pk_mul_f32 v[164:165], v[20:21], v[148:149]
	v_pk_mul_f32 v[166:167], v[18:19], v[146:147]
	v_max_f32_e64 v164, |v164|, |v165|
	v_max_f32_e64 v166, |v166|, |v167|
	v_max3_f32 v168, v168, v166, v164
	s_waitcnt vmcnt(2)
	v_pk_mul_f32 v[164:165], v[48:49], v[136:137]
	v_pk_mul_f32 v[166:167], v[46:47], v[134:135]
	v_max_f32_e64 v164, |v164|, |v165|
	v_max_f32_e64 v166, |v166|, |v167|
	v_max3_f32 v168, v168, v166, v164
	v_pk_mul_f32 v[164:165], v[40:41], v[132:133]
	v_pk_mul_f32 v[166:167], v[38:39], v[130:131]
	v_max_f32_e64 v164, |v164|, |v165|
	v_max_f32_e64 v166, |v166|, |v167|
	v_max3_f32 v166, v168, v166, v164
	v_mul_f32_e32 v164, v27, v27
	v_mul_f32_e32 v165, v29, v29
	v_fmac_f32_e32 v164, v26, v26
	v_fmac_f32_e32 v165, v28, v28
	v_add_f32_e32 v164, v164, v165
	v_mul_f32_e32 v165, v19, v19
	v_mul_f32_e32 v167, v21, v21
	v_fmac_f32_e32 v165, v18, v18
	v_fmac_f32_e32 v167, v20, v20
	v_add_f32_e32 v165, v165, v167
	v_add_f32_e32 v164, v164, v165
	v_mul_f32_e32 v165, v47, v47
	v_mul_f32_e32 v167, v49, v49
	v_fmac_f32_e32 v165, v46, v46
	v_fmac_f32_e32 v167, v48, v48
	v_add_f32_e32 v165, v165, v167
	v_add_f32_e32 v164, v165, v164
	v_mul_f32_e32 v165, v39, v39
	v_mul_f32_e32 v167, v41, v41
	v_fmac_f32_e32 v165, v38, v38
	v_fmac_f32_e32 v167, v40, v40
	v_add_f32_e32 v165, v165, v167
	v_add_f32_e32 v164, v165, v164
	v_mov_b32_e32 v167, v166
	v_mov_b32_e32 v165, v164
	s_nop 1
	v_permlane16_swap_b32_e32 v167, v166
	v_permlane16_swap_b32_e32 v165, v164
	s_waitcnt lgkmcnt(1)
	v_max_f32_e32 v167, v167, v167
	s_waitcnt lgkmcnt(0)
	v_add_f32_e32 v164, v164, v165
	v_max_f32_e32 v166, v166, v167
	v_mov_b32_e32 v165, v164
	v_mov_b32_e32 v167, v166
	s_nop 1
	v_permlane32_swap_b32_e32 v165, v164
	v_permlane32_swap_b32_e32 v167, v166
	s_and_saveexec_b64 s[6:7], s[8:9]
	s_cbranch_execz .LBB0_548
	s_lshl_b32 s18, s57, 11
	s_add_i32 s18, s37, s18
	s_waitcnt lgkmcnt(1)
	v_add_f32_e32 v164, v164, v165
	s_waitcnt lgkmcnt(0)
	v_max_f32_e32 v165, v167, v167
	v_max_f32_e32 v166, v166, v166
	v_lshl_add_u32 v168, v219, 5, s18
	v_max_f32_e32 v165, v166, v165
	ds_write_b64 v168, v[164:165]
.LBB0_548:
	s_or_b64 exec, exec, s[6:7]
	s_waitcnt lgkmcnt(1)
	v_pk_mul_f32 v[164:165], v[44:45], v[140:141]
	s_waitcnt lgkmcnt(0)
	v_pk_mul_f32 v[166:167], v[42:43], v[138:139]
	v_max_f32_e64 v164, |v164|, |v165|
	v_max_f32_e64 v166, |v166|, |v167|
	v_max3_f32 v168, v166, 0, v164
	v_pk_mul_f32 v[164:165], v[36:37], v[148:149]
	v_pk_mul_f32 v[166:167], v[34:35], v[146:147]
	v_max_f32_e64 v164, |v164|, |v165|
	v_max_f32_e64 v166, |v166|, |v167|
	v_max3_f32 v168, v168, v166, v164
	v_pk_mul_f32 v[164:165], v[64:65], v[136:137]
	v_pk_mul_f32 v[166:167], v[62:63], v[134:135]
	v_max_f32_e64 v164, |v164|, |v165|
	v_max_f32_e64 v166, |v166|, |v167|
	v_max3_f32 v168, v168, v166, v164
	v_pk_mul_f32 v[164:165], v[60:61], v[132:133]
	v_pk_mul_f32 v[166:167], v[58:59], v[130:131]
	v_max_f32_e64 v164, |v164|, |v165|
	v_max_f32_e64 v166, |v166|, |v167|
	v_max3_f32 v166, v168, v166, v164
	v_mul_f32_e32 v164, v43, v43
	v_mul_f32_e32 v165, v45, v45
	v_fmac_f32_e32 v164, v42, v42
	v_fmac_f32_e32 v165, v44, v44
	v_add_f32_e32 v164, v164, v165
	v_mul_f32_e32 v165, v35, v35
	v_mul_f32_e32 v167, v37, v37
	v_fmac_f32_e32 v165, v34, v34
	v_fmac_f32_e32 v167, v36, v36
	v_add_f32_e32 v165, v165, v167
	v_add_f32_e32 v164, v164, v165
	v_mul_f32_e32 v165, v63, v63
	v_mul_f32_e32 v167, v65, v65
	v_fmac_f32_e32 v165, v62, v62
	v_fmac_f32_e32 v167, v64, v64
	v_add_f32_e32 v165, v165, v167
	v_add_f32_e32 v164, v165, v164
	v_mul_f32_e32 v165, v59, v59
	v_mul_f32_e32 v167, v61, v61
	v_fmac_f32_e32 v165, v58, v58
	v_fmac_f32_e32 v167, v60, v60
	v_add_f32_e32 v165, v165, v167
	v_add_f32_e32 v164, v165, v164
	v_mov_b32_e32 v167, v166
	v_mov_b32_e32 v165, v164
	s_nop 1
	v_permlane16_swap_b32_e32 v167, v166
	v_permlane16_swap_b32_e32 v165, v164
	s_waitcnt lgkmcnt(1)
	v_max_f32_e32 v167, v167, v167
	s_waitcnt lgkmcnt(0)
	v_add_f32_e32 v164, v164, v165
	v_max_f32_e32 v166, v166, v167
	v_mov_b32_e32 v165, v164
	v_mov_b32_e32 v167, v166
	s_nop 1
	v_permlane32_swap_b32_e32 v165, v164
	v_permlane32_swap_b32_e32 v167, v166
	s_and_saveexec_b64 s[6:7], s[8:9]
	s_cbranch_execz .LBB0_550
	s_lshl_b32 s18, s57, 11
	s_add_i32 s18, s37, s18
	s_waitcnt lgkmcnt(1)
	v_add_f32_e32 v164, v164, v165
	s_waitcnt lgkmcnt(0)
	v_max_f32_e32 v165, v167, v167
	v_max_f32_e32 v166, v166, v166
	v_lshl_add_u32 v168, v219, 5, s18
	v_max_f32_e32 v165, v166, v165
	ds_write_b64 v168, v[164:165] offset:512
.LBB0_550:
	s_or_b64 exec, exec, s[6:7]
	s_waitcnt lgkmcnt(1)
	v_pk_mul_f32 v[164:165], v[56:57], v[140:141]
	s_waitcnt lgkmcnt(0)
	v_pk_mul_f32 v[166:167], v[54:55], v[138:139]
	v_max_f32_e64 v164, |v164|, |v165|
	v_max_f32_e64 v166, |v166|, |v167|
	v_max3_f32 v168, v166, 0, v164
	v_pk_mul_f32 v[164:165], v[52:53], v[148:149]
	v_pk_mul_f32 v[166:167], v[50:51], v[146:147]
	v_max_f32_e64 v164, |v164|, |v165|
	v_max_f32_e64 v166, |v166|, |v167|
	v_max3_f32 v168, v168, v166, v164
	v_pk_mul_f32 v[164:165], v[88:89], v[136:137]
	v_pk_mul_f32 v[166:167], v[86:87], v[134:135]
	v_max_f32_e64 v164, |v164|, |v165|
	v_max_f32_e64 v166, |v166|, |v167|
	v_max3_f32 v168, v168, v166, v164
	v_pk_mul_f32 v[164:165], v[84:85], v[132:133]
	v_pk_mul_f32 v[166:167], v[82:83], v[130:131]
	v_max_f32_e64 v164, |v164|, |v165|
	v_max_f32_e64 v166, |v166|, |v167|
	v_max3_f32 v166, v168, v166, v164
	v_mul_f32_e32 v164, v55, v55
	v_mul_f32_e32 v165, v57, v57
	v_fmac_f32_e32 v164, v54, v54
	v_fmac_f32_e32 v165, v56, v56
	v_add_f32_e32 v164, v164, v165
	v_mul_f32_e32 v165, v51, v51
	v_mul_f32_e32 v167, v53, v53
	v_fmac_f32_e32 v165, v50, v50
	v_fmac_f32_e32 v167, v52, v52
	v_add_f32_e32 v165, v165, v167
	v_add_f32_e32 v164, v164, v165
	v_mul_f32_e32 v165, v87, v87
	v_mul_f32_e32 v167, v89, v89
	v_fmac_f32_e32 v165, v86, v86
	v_fmac_f32_e32 v167, v88, v88
	v_add_f32_e32 v165, v165, v167
	v_add_f32_e32 v164, v165, v164
	v_mul_f32_e32 v165, v83, v83
	v_mul_f32_e32 v167, v85, v85
	v_fmac_f32_e32 v165, v82, v82
	v_fmac_f32_e32 v167, v84, v84
	v_add_f32_e32 v165, v165, v167
	v_add_f32_e32 v164, v165, v164
	v_mov_b32_e32 v167, v166
	v_mov_b32_e32 v165, v164
	s_nop 1
	v_permlane16_swap_b32_e32 v167, v166
	v_permlane16_swap_b32_e32 v165, v164
	s_waitcnt lgkmcnt(1)
	v_max_f32_e32 v167, v167, v167
	s_waitcnt lgkmcnt(0)
	v_add_f32_e32 v164, v164, v165
	v_max_f32_e32 v166, v166, v167
	v_mov_b32_e32 v165, v164
	v_mov_b32_e32 v167, v166
	s_nop 1
	v_permlane32_swap_b32_e32 v165, v164
	v_permlane32_swap_b32_e32 v167, v166
	s_and_saveexec_b64 s[6:7], s[8:9]
	s_cbranch_execz .LBB0_552
	s_lshl_b32 s18, s57, 11
	s_add_i32 s18, s37, s18
	s_waitcnt lgkmcnt(1)
	v_add_f32_e32 v164, v164, v165
	s_waitcnt lgkmcnt(0)
	v_max_f32_e32 v165, v167, v167
	v_max_f32_e32 v166, v166, v166
	v_lshl_add_u32 v168, v219, 5, s18
	v_max_f32_e32 v165, v166, v165
	ds_write_b64 v168, v[164:165] offset:1024
.LBB0_552:
	s_or_b64 exec, exec, s[6:7]
	s_waitcnt lgkmcnt(1)
	v_pk_mul_f32 v[164:165], v[80:81], v[140:141]
	s_waitcnt lgkmcnt(0)
	v_pk_mul_f32 v[166:167], v[78:79], v[138:139]
	v_max_f32_e64 v164, |v164|, |v165|
	v_max_f32_e64 v166, |v166|, |v167|
	v_max3_f32 v168, v166, 0, v164
	v_pk_mul_f32 v[164:165], v[72:73], v[148:149]
	v_pk_mul_f32 v[166:167], v[70:71], v[146:147]
	v_max_f32_e64 v164, |v164|, |v165|
	v_max_f32_e64 v166, |v166|, |v167|
	v_max3_f32 v168, v168, v166, v164
	v_pk_mul_f32 v[164:165], v[104:105], v[136:137]
	v_pk_mul_f32 v[166:167], v[102:103], v[134:135]
	v_max_f32_e64 v164, |v164|, |v165|
	v_max_f32_e64 v166, |v166|, |v167|
	v_max3_f32 v168, v168, v166, v164
	v_pk_mul_f32 v[164:165], v[100:101], v[132:133]
	v_pk_mul_f32 v[166:167], v[98:99], v[130:131]
	v_max_f32_e64 v164, |v164|, |v165|
	v_max_f32_e64 v166, |v166|, |v167|
	v_max3_f32 v166, v168, v166, v164
	v_mul_f32_e32 v164, v79, v79
	v_mul_f32_e32 v165, v81, v81
	v_fmac_f32_e32 v164, v78, v78
	v_fmac_f32_e32 v165, v80, v80
	v_add_f32_e32 v164, v164, v165
	v_mul_f32_e32 v165, v71, v71
	v_mul_f32_e32 v167, v73, v73
	v_fmac_f32_e32 v165, v70, v70
	v_fmac_f32_e32 v167, v72, v72
	v_add_f32_e32 v165, v165, v167
	v_add_f32_e32 v164, v164, v165
	v_mul_f32_e32 v165, v103, v103
	v_mul_f32_e32 v167, v105, v105
	v_fmac_f32_e32 v165, v102, v102
	v_fmac_f32_e32 v167, v104, v104
	v_add_f32_e32 v165, v165, v167
	v_add_f32_e32 v164, v165, v164
	v_mul_f32_e32 v165, v99, v99
	v_mul_f32_e32 v167, v101, v101
	v_fmac_f32_e32 v165, v98, v98
	v_fmac_f32_e32 v167, v100, v100
	v_add_f32_e32 v165, v165, v167
	v_add_f32_e32 v164, v165, v164
	v_mov_b32_e32 v167, v166
	v_mov_b32_e32 v165, v164
	s_nop 1
	v_permlane16_swap_b32_e32 v167, v166
	v_permlane16_swap_b32_e32 v165, v164
	s_waitcnt lgkmcnt(1)
	v_max_f32_e32 v167, v167, v167
	s_waitcnt lgkmcnt(0)
	v_add_f32_e32 v164, v164, v165
	v_max_f32_e32 v166, v166, v167
	v_mov_b32_e32 v165, v164
	v_mov_b32_e32 v167, v166
	s_nop 1
	v_permlane32_swap_b32_e32 v165, v164
	v_permlane32_swap_b32_e32 v167, v166
	s_and_saveexec_b64 s[6:7], s[8:9]
	s_cbranch_execz .LBB0_554
	s_lshl_b32 s18, s57, 11
	s_add_i32 s18, s37, s18
	s_waitcnt lgkmcnt(1)
	v_add_f32_e32 v164, v164, v165
	s_waitcnt lgkmcnt(0)
	v_max_f32_e32 v165, v167, v167
	v_max_f32_e32 v166, v166, v166
	v_lshl_add_u32 v168, v219, 5, s18
	v_max_f32_e32 v165, v166, v165
	ds_write_b64 v168, v[164:165] offset:1536
.LBB0_554:
	s_or_b64 exec, exec, s[6:7]
	s_waitcnt lgkmcnt(1)
	v_pk_mul_f32 v[164:165], v[96:97], v[140:141]
	s_waitcnt lgkmcnt(0)
	v_pk_mul_f32 v[166:167], v[94:95], v[138:139]
	v_max_f32_e64 v164, |v164|, |v165|
	v_max_f32_e64 v166, |v166|, |v167|
	v_max3_f32 v168, v166, 0, v164
	v_pk_mul_f32 v[164:165], v[92:93], v[148:149]
	v_pk_mul_f32 v[166:167], v[90:91], v[146:147]
	v_max_f32_e64 v164, |v164|, |v165|
	v_max_f32_e64 v166, |v166|, |v167|
	v_max3_f32 v168, v168, v166, v164
	v_pk_mul_f32 v[164:165], v[128:129], v[136:137]
	v_pk_mul_f32 v[166:167], v[126:127], v[134:135]
	v_max_f32_e64 v164, |v164|, |v165|
	v_max_f32_e64 v166, |v166|, |v167|
	v_max3_f32 v168, v168, v166, v164
	v_pk_mul_f32 v[164:165], v[120:121], v[132:133]
	v_pk_mul_f32 v[166:167], v[118:119], v[130:131]
	v_max_f32_e64 v164, |v164|, |v165|
	v_max_f32_e64 v166, |v166|, |v167|
	v_max3_f32 v166, v168, v166, v164
	v_mul_f32_e32 v164, v95, v95
	v_mul_f32_e32 v165, v97, v97
	v_fmac_f32_e32 v164, v94, v94
	v_fmac_f32_e32 v165, v96, v96
	v_add_f32_e32 v164, v164, v165
	v_mul_f32_e32 v165, v91, v91
	v_mul_f32_e32 v167, v93, v93
	v_fmac_f32_e32 v165, v90, v90
	v_fmac_f32_e32 v167, v92, v92
	v_add_f32_e32 v165, v165, v167
	v_add_f32_e32 v164, v164, v165
	v_mul_f32_e32 v165, v127, v127
	v_mul_f32_e32 v167, v129, v129
	v_fmac_f32_e32 v165, v126, v126
	v_fmac_f32_e32 v167, v128, v128
	v_add_f32_e32 v165, v165, v167
	v_add_f32_e32 v164, v165, v164
	v_mul_f32_e32 v165, v119, v119
	v_mul_f32_e32 v167, v121, v121
	v_fmac_f32_e32 v165, v118, v118
	v_fmac_f32_e32 v167, v120, v120
	v_add_f32_e32 v165, v165, v167
	v_add_f32_e32 v164, v165, v164
	v_mov_b32_e32 v167, v166
	v_mov_b32_e32 v165, v164
	s_nop 1
	v_permlane16_swap_b32_e32 v167, v166
	v_permlane16_swap_b32_e32 v165, v164
	s_waitcnt lgkmcnt(1)
	v_max_f32_e32 v167, v167, v167
	s_waitcnt lgkmcnt(0)
	v_add_f32_e32 v164, v164, v165
	v_max_f32_e32 v166, v166, v167
	v_mov_b32_e32 v165, v164
	v_mov_b32_e32 v167, v166
	s_nop 1
	v_permlane32_swap_b32_e32 v165, v164
	v_permlane32_swap_b32_e32 v167, v166
	s_and_saveexec_b64 s[6:7], s[8:9]
	s_cbranch_execz .LBB0_556
	s_lshl_b32 s18, s57, 11
	s_add_i32 s18, s37, s18
	s_waitcnt lgkmcnt(1)
	v_add_f32_e32 v164, v164, v165
	s_waitcnt lgkmcnt(0)
	v_max_f32_e32 v165, v167, v167
	v_max_f32_e32 v166, v166, v166
	v_lshl_add_u32 v168, v219, 5, s18
	v_max_f32_e32 v165, v166, v165
	ds_write_b64 v168, v[164:165] offset:4096
.LBB0_556:
	s_or_b64 exec, exec, s[6:7]
	s_waitcnt lgkmcnt(1)
	v_pk_mul_f32 v[164:165], v[116:117], v[140:141]
	s_waitcnt lgkmcnt(0)
	v_pk_mul_f32 v[166:167], v[114:115], v[138:139]
	v_max_f32_e64 v164, |v164|, |v165|
	v_max_f32_e64 v166, |v166|, |v167|
	v_max3_f32 v168, v166, 0, v164
	v_pk_mul_f32 v[164:165], v[108:109], v[148:149]
	v_pk_mul_f32 v[166:167], v[106:107], v[146:147]
	v_max_f32_e64 v164, |v164|, |v165|
	v_max_f32_e64 v166, |v166|, |v167|
	v_max3_f32 v168, v168, v166, v164
	v_pk_mul_f32 v[164:165], v[124:125], v[136:137]
	v_pk_mul_f32 v[166:167], v[122:123], v[134:135]
	v_max_f32_e64 v164, |v164|, |v165|
	v_max_f32_e64 v166, |v166|, |v167|
	v_max3_f32 v168, v168, v166, v164
	v_pk_mul_f32 v[164:165], v[112:113], v[132:133]
	v_pk_mul_f32 v[166:167], v[110:111], v[130:131]
	v_max_f32_e64 v164, |v164|, |v165|
	v_max_f32_e64 v166, |v166|, |v167|
	v_max3_f32 v166, v168, v166, v164
	v_mul_f32_e32 v164, v115, v115
	v_mul_f32_e32 v165, v117, v117
	v_fmac_f32_e32 v164, v114, v114
	v_fmac_f32_e32 v165, v116, v116
	v_add_f32_e32 v164, v164, v165
	v_mul_f32_e32 v165, v107, v107
	v_mul_f32_e32 v167, v109, v109
	v_fmac_f32_e32 v165, v106, v106
	v_fmac_f32_e32 v167, v108, v108
	v_add_f32_e32 v165, v165, v167
	v_add_f32_e32 v164, v164, v165
	v_mul_f32_e32 v165, v123, v123
	v_mul_f32_e32 v167, v125, v125
	v_fmac_f32_e32 v165, v122, v122
	v_fmac_f32_e32 v167, v124, v124
	v_add_f32_e32 v165, v165, v167
	v_add_f32_e32 v164, v165, v164
	v_mul_f32_e32 v165, v111, v111
	v_mul_f32_e32 v167, v113, v113
	v_fmac_f32_e32 v165, v110, v110
	v_fmac_f32_e32 v167, v112, v112
	v_add_f32_e32 v165, v165, v167
	v_add_f32_e32 v164, v165, v164
	v_mov_b32_e32 v167, v166
	v_mov_b32_e32 v165, v164
	s_nop 1
	v_permlane16_swap_b32_e32 v167, v166
	v_permlane16_swap_b32_e32 v165, v164
	s_waitcnt lgkmcnt(1)
	v_max_f32_e32 v167, v167, v167
	s_waitcnt lgkmcnt(0)
	v_add_f32_e32 v164, v164, v165
	v_max_f32_e32 v166, v166, v167
	v_mov_b32_e32 v165, v164
	v_mov_b32_e32 v167, v166
	s_nop 1
	v_permlane32_swap_b32_e32 v165, v164
	v_permlane32_swap_b32_e32 v167, v166
	s_and_saveexec_b64 s[6:7], s[8:9]
	s_cbranch_execz .LBB0_558
	s_lshl_b32 s18, s57, 11
	s_add_i32 s18, s37, s18
	s_waitcnt lgkmcnt(1)
	v_add_f32_e32 v164, v164, v165
	s_waitcnt lgkmcnt(0)
	v_max_f32_e32 v165, v167, v167
	v_max_f32_e32 v166, v166, v166
	v_lshl_add_u32 v168, v219, 5, s18
	v_max_f32_e32 v165, v166, v165
	ds_write_b64 v168, v[164:165] offset:4608
.LBB0_558:
	s_or_b64 exec, exec, s[6:7]
	s_waitcnt lgkmcnt(1)
	v_pk_mul_f32 v[164:165], v[76:77], v[140:141]
	s_waitcnt lgkmcnt(0)
	v_pk_mul_f32 v[166:167], v[74:75], v[138:139]
	v_max_f32_e64 v164, |v164|, |v165|
	v_max_f32_e64 v166, |v166|, |v167|
	v_max3_f32 v168, v166, 0, v164
	v_pk_mul_f32 v[164:165], v[68:69], v[148:149]
	v_pk_mul_f32 v[166:167], v[66:67], v[146:147]
	v_max_f32_e64 v164, |v164|, |v165|
	v_max_f32_e64 v166, |v166|, |v167|
	v_max3_f32 v168, v168, v166, v164
	v_pk_mul_f32 v[164:165], v[32:33], v[136:137]
	v_pk_mul_f32 v[166:167], v[30:31], v[134:135]
	v_max_f32_e64 v164, |v164|, |v165|
	v_max_f32_e64 v166, |v166|, |v167|
	v_max3_f32 v168, v168, v166, v164
	v_pk_mul_f32 v[164:165], v[24:25], v[132:133]
	v_pk_mul_f32 v[166:167], v[22:23], v[130:131]
	v_max_f32_e64 v164, |v164|, |v165|
	v_max_f32_e64 v166, |v166|, |v167|
	v_max3_f32 v166, v168, v166, v164
	v_mul_f32_e32 v164, v75, v75
	v_mul_f32_e32 v165, v77, v77
	v_fmac_f32_e32 v164, v74, v74
	v_fmac_f32_e32 v165, v76, v76
	v_add_f32_e32 v164, v164, v165
	v_mul_f32_e32 v165, v67, v67
	v_mul_f32_e32 v167, v69, v69
	v_fmac_f32_e32 v165, v66, v66
	v_fmac_f32_e32 v167, v68, v68
	v_add_f32_e32 v165, v165, v167
	v_add_f32_e32 v164, v164, v165
	v_mul_f32_e32 v165, v31, v31
	v_mul_f32_e32 v167, v33, v33
	v_fmac_f32_e32 v165, v30, v30
	v_fmac_f32_e32 v167, v32, v32
	v_add_f32_e32 v165, v165, v167
	v_add_f32_e32 v164, v165, v164
	v_mul_f32_e32 v165, v23, v23
	v_mul_f32_e32 v167, v25, v25
	v_fmac_f32_e32 v165, v22, v22
	v_fmac_f32_e32 v167, v24, v24
	v_add_f32_e32 v165, v165, v167
	v_add_f32_e32 v164, v165, v164
	v_mov_b32_e32 v167, v166
	v_mov_b32_e32 v165, v164
	s_nop 1
	v_permlane16_swap_b32_e32 v167, v166
	v_permlane16_swap_b32_e32 v165, v164
	s_waitcnt lgkmcnt(1)
	v_max_f32_e32 v167, v167, v167
	s_waitcnt lgkmcnt(0)
	v_add_f32_e32 v164, v164, v165
	v_max_f32_e32 v166, v166, v167
	v_mov_b32_e32 v165, v164
	v_mov_b32_e32 v167, v166
	s_nop 1
	v_permlane32_swap_b32_e32 v165, v164
	v_permlane32_swap_b32_e32 v167, v166
	s_and_saveexec_b64 s[6:7], s[8:9]
	s_cbranch_execz .LBB0_560
	s_lshl_b32 s18, s57, 11
	s_add_i32 s18, s37, s18
	s_waitcnt lgkmcnt(1)
	v_add_f32_e32 v164, v164, v165
	s_waitcnt lgkmcnt(0)
	v_max_f32_e32 v165, v167, v167
	v_max_f32_e32 v166, v166, v166
	v_lshl_add_u32 v168, v219, 5, s18
	v_max_f32_e32 v165, v166, v165
	ds_write_b64 v168, v[164:165] offset:5120
.LBB0_560:
	s_or_b64 exec, exec, s[6:7]
	s_waitcnt lgkmcnt(1)
	v_pk_mul_f32 v[164:165], v[16:17], v[140:141]
	s_waitcnt lgkmcnt(0)
	v_pk_mul_f32 v[166:167], v[14:15], v[138:139]
	v_max_f32_e64 v164, |v164|, |v165|
	v_max_f32_e64 v166, |v166|, |v167|
	v_max3_f32 v168, v166, 0, v164
	v_pk_mul_f32 v[164:165], v[12:13], v[148:149]
	v_pk_mul_f32 v[166:167], v[10:11], v[146:147]
	v_max_f32_e64 v164, |v164|, |v165|
	v_max_f32_e64 v166, |v166|, |v167|
	v_max3_f32 v168, v168, v166, v164
	v_pk_mul_f32 v[164:165], v[8:9], v[136:137]
	v_pk_mul_f32 v[166:167], v[6:7], v[134:135]
	v_max_f32_e64 v164, |v164|, |v165|
	v_max_f32_e64 v166, |v166|, |v167|
	v_max3_f32 v168, v168, v166, v164
	v_pk_mul_f32 v[164:165], v[4:5], v[132:133]
	v_pk_mul_f32 v[166:167], v[2:3], v[130:131]
	v_max_f32_e64 v164, |v164|, |v165|
	v_max_f32_e64 v166, |v166|, |v167|
	v_max3_f32 v166, v168, v166, v164
	v_mul_f32_e32 v164, v15, v15
	v_mul_f32_e32 v165, v17, v17
	v_fmac_f32_e32 v164, v14, v14
	v_fmac_f32_e32 v165, v16, v16
	v_add_f32_e32 v164, v164, v165
	v_mul_f32_e32 v165, v11, v11
	v_mul_f32_e32 v167, v13, v13
	v_fmac_f32_e32 v165, v10, v10
	v_fmac_f32_e32 v167, v12, v12
	v_add_f32_e32 v165, v165, v167
	v_add_f32_e32 v164, v164, v165
	v_mul_f32_e32 v165, v7, v7
	v_mul_f32_e32 v167, v9, v9
	v_fmac_f32_e32 v165, v6, v6
	v_fmac_f32_e32 v167, v8, v8
	v_add_f32_e32 v165, v165, v167
	v_add_f32_e32 v164, v165, v164
	v_mul_f32_e32 v165, v3, v3
	v_mul_f32_e32 v167, v5, v5
	v_fmac_f32_e32 v165, v2, v2
	v_fmac_f32_e32 v167, v4, v4
	v_add_f32_e32 v165, v165, v167
	v_add_f32_e32 v164, v165, v164
	v_mov_b32_e32 v167, v166
	v_mov_b32_e32 v165, v164
	s_nop 1
	v_permlane16_swap_b32_e32 v167, v166
	v_permlane16_swap_b32_e32 v165, v164
	s_waitcnt lgkmcnt(1)
	v_max_f32_e32 v167, v167, v167
	s_waitcnt lgkmcnt(0)
	v_add_f32_e32 v164, v164, v165
	v_max_f32_e32 v166, v166, v167
	v_mov_b32_e32 v165, v164
	v_mov_b32_e32 v167, v166
	s_nop 1
	v_permlane32_swap_b32_e32 v165, v164
	v_permlane32_swap_b32_e32 v167, v166
	s_and_saveexec_b64 s[6:7], s[8:9]
	s_cbranch_execz .LBB0_562
	s_lshl_b32 s8, s57, 11
	s_add_i32 s37, s37, s8
	s_waitcnt lgkmcnt(1)
	v_add_f32_e32 v164, v164, v165
	s_waitcnt lgkmcnt(0)
	v_max_f32_e32 v165, v167, v167
	v_max_f32_e32 v166, v166, v166
	v_lshl_add_u32 v168, v219, 5, s37
	v_max_f32_e32 v165, v166, v165
	ds_write_b64 v168, v[164:165] offset:5632

.LBB0_1196:
	s_mul_i32 s6, s94, 0x6000
	s_add_u32 s64, s12, s6
	s_mul_hi_u32 s6, s94, 0x6000
	s_addc_u32 s65, s11, s6
	v_lshlrev_b32_e32 v222, 2, v239
	v_lshl_add_u64 v[134:135], s[64:65], 0, v[222:223]
	s_mov_b64 s[6:7], 0x4000
	v_lshl_add_u64 v[138:139], v[134:135], 0, s[6:7]
	s_movk_i32 s6, 0x4000
	v_add_co_u32_e32 v134, vcc, s6, v134
	v_and_b32_e32 v212, 64, v244
	s_nop 0
	v_addc_co_u32_e32 v135, vcc, 0, v135, vcc
	global_load_dwordx4 v[150:153], v[134:135], off
	s_nop 0
	global_load_dwordx4 v[134:137], v[138:139], off offset:528
	global_load_dwordx4 v[146:149], v[138:139], off offset:16
	s_nop 0
	global_load_dwordx4 v[138:141], v[138:139], off offset:512
	v_xor_b32_e32 v211, 16, v244
	v_add_u32_e32 v212, 64, v212
	v_cmp_lt_i32_e32 vcc, v211, v212
	v_mul_f32_e32 v213, v33, v33
	v_fmac_f32_e32 v213, v32, v32
	v_cndmask_b32_e32 v211, v244, v211, vcc
	v_lshlrev_b32_e32 v237, 2, v211
	v_mul_f32_e32 v211, v31, v31
	v_fmac_f32_e32 v211, v30, v30
	v_add_f32_e32 v211, v211, v213
	v_mul_f32_e32 v213, v27, v27
	v_mul_f32_e32 v214, v29, v29
	v_fmac_f32_e32 v213, v26, v26
	v_fmac_f32_e32 v214, v28, v28
	v_add_f32_e32 v213, v213, v214
	v_add_f32_e32 v211, v211, v213
	v_mul_f32_e32 v213, v43, v43
	v_mul_f32_e32 v214, v45, v45
	v_fmac_f32_e32 v213, v42, v42
	v_fmac_f32_e32 v214, v44, v44
	v_add_f32_e32 v213, v213, v214
	v_add_f32_e32 v211, v211, v213
	v_mul_f32_e32 v213, v35, v35
	v_mul_f32_e32 v214, v37, v37
	v_fmac_f32_e32 v213, v34, v34
	v_fmac_f32_e32 v214, v36, v36
	v_add_f32_e32 v213, v213, v214
	v_add_f32_e32 v211, v211, v213
	v_mov_b32_e32 v213, v211
	s_nop 1
	v_permlane16_swap_b32_e32 v213, v211
	v_xor_b32_e32 v214, 32, v244
	v_cmp_lt_i32_e32 vcc, v214, v212
	s_lshl_b32 s8, s55, 3
	s_add_i32 s45, s8, 0
	v_cndmask_b32_e32 v212, v244, v214, vcc
	v_lshlrev_b32_e32 v238, 2, v212
	s_waitcnt lgkmcnt(0)
	v_add_f32_e32 v212, v211, v213
	v_mov_b32_e32 v213, v212
	s_nop 1
	v_permlane32_swap_b32_e32 v213, v212
	v_and_b32_e32 v211, 63, v210
	v_cmp_gt_u32_e64 s[6:7], 16, v211
	s_and_saveexec_b64 s[8:9], s[6:7]
	s_cbranch_execz .LBB0_1198
	s_lshl_b32 s11, s83, 11
	s_add_i32 s11, s45, s11
	v_lshl_add_u32 v214, v219, 5, s11
	s_waitcnt lgkmcnt(0)
	v_add_f32_e32 v212, v212, v213
	v_mov_b32_e32 v213, v223
	ds_write_b64 v214, v[212:213]
.LBB0_1198:
	s_or_b64 exec, exec, s[8:9]
	v_mul_f32_e32 v212, v55, v55
	s_waitcnt lgkmcnt(0)
	v_mul_f32_e32 v213, v57, v57
	v_fmac_f32_e32 v212, v54, v54
	v_fmac_f32_e32 v213, v56, v56
	v_add_f32_e32 v212, v212, v213
	v_mul_f32_e32 v213, v51, v51
	v_mul_f32_e32 v214, v53, v53
	v_fmac_f32_e32 v213, v50, v50
	v_fmac_f32_e32 v214, v52, v52
	v_add_f32_e32 v213, v213, v214
	v_add_f32_e32 v212, v212, v213
	v_mul_f32_e32 v213, v67, v67
	v_mul_f32_e32 v214, v69, v69
	v_fmac_f32_e32 v213, v66, v66
	v_fmac_f32_e32 v214, v68, v68
	v_add_f32_e32 v213, v213, v214
	v_add_f32_e32 v212, v212, v213
	v_mul_f32_e32 v213, v59, v59
	v_mul_f32_e32 v214, v61, v61
	v_fmac_f32_e32 v213, v58, v58
	v_fmac_f32_e32 v214, v60, v60
	v_add_f32_e32 v213, v213, v214
	v_add_f32_e32 v212, v212, v213
	v_mov_b32_e32 v213, v212
	s_nop 1
	v_permlane16_swap_b32_e32 v213, v212
	s_waitcnt lgkmcnt(0)
	v_add_f32_e32 v212, v212, v213
	v_mov_b32_e32 v213, v212
	s_nop 1
	v_permlane32_swap_b32_e32 v213, v212
	s_and_saveexec_b64 s[8:9], s[6:7]
	s_cbranch_execz .LBB0_1200
	s_lshl_b32 s11, s83, 11
	s_add_i32 s11, s45, s11
	v_lshl_add_u32 v214, v219, 5, s11
	s_waitcnt lgkmcnt(0)
	v_add_f32_e32 v212, v212, v213
	v_mov_b32_e32 v213, v223
	ds_write_b64 v214, v[212:213] offset:512
.LBB0_1200:
	s_or_b64 exec, exec, s[8:9]
	v_mul_f32_e32 v212, v79, v79
	s_waitcnt lgkmcnt(0)
	v_mul_f32_e32 v213, v81, v81
	v_fmac_f32_e32 v212, v78, v78
	v_fmac_f32_e32 v213, v80, v80
	v_add_f32_e32 v212, v212, v213
	v_mul_f32_e32 v213, v75, v75
	v_mul_f32_e32 v214, v77, v77
	v_fmac_f32_e32 v213, v74, v74
	v_fmac_f32_e32 v214, v76, v76
	v_add_f32_e32 v213, v213, v214
	v_add_f32_e32 v212, v212, v213
	v_mul_f32_e32 v213, v87, v87
	v_mul_f32_e32 v214, v89, v89
	v_fmac_f32_e32 v213, v86, v86
	v_fmac_f32_e32 v214, v88, v88
	v_add_f32_e32 v213, v213, v214
	v_add_f32_e32 v212, v212, v213
	v_mul_f32_e32 v213, v83, v83
	v_mul_f32_e32 v214, v85, v85
	v_fmac_f32_e32 v213, v82, v82
	v_fmac_f32_e32 v214, v84, v84
	v_add_f32_e32 v213, v213, v214
	v_add_f32_e32 v212, v212, v213
	v_mov_b32_e32 v213, v212
	s_nop 1
	v_permlane16_swap_b32_e32 v213, v212
	s_waitcnt lgkmcnt(0)
	v_add_f32_e32 v212, v212, v213
	v_mov_b32_e32 v213, v212
	s_nop 1
	v_permlane32_swap_b32_e32 v213, v212
	s_and_saveexec_b64 s[8:9], s[6:7]
	s_cbranch_execz .LBB0_1202
	s_lshl_b32 s11, s83, 11
	s_add_i32 s11, s45, s11
	v_lshl_add_u32 v214, v219, 5, s11
	s_waitcnt lgkmcnt(0)
	v_add_f32_e32 v212, v212, v213
	v_mov_b32_e32 v213, v223
	ds_write_b64 v214, v[212:213] offset:1024
.LBB0_1202:
	s_or_b64 exec, exec, s[8:9]
	v_mul_f32_e32 v212, v103, v103
	s_waitcnt lgkmcnt(0)
	v_mul_f32_e32 v213, v105, v105
	v_fmac_f32_e32 v212, v102, v102
	v_fmac_f32_e32 v213, v104, v104
	v_add_f32_e32 v212, v212, v213
	v_mul_f32_e32 v213, v95, v95
	v_mul_f32_e32 v214, v97, v97
	v_fmac_f32_e32 v213, v94, v94
	v_fmac_f32_e32 v214, v96, v96
	v_add_f32_e32 v213, v213, v214
	v_add_f32_e32 v212, v212, v213
	v_mul_f32_e32 v213, v111, v111
	v_mul_f32_e32 v214, v113, v113
	v_fmac_f32_e32 v213, v110, v110
	v_fmac_f32_e32 v214, v112, v112
	v_add_f32_e32 v213, v213, v214
	v_add_f32_e32 v212, v212, v213
	v_mul_f32_e32 v213, v107, v107
	v_mul_f32_e32 v214, v109, v109
	v_fmac_f32_e32 v213, v106, v106
	v_fmac_f32_e32 v214, v108, v108
	v_add_f32_e32 v213, v213, v214
	v_add_f32_e32 v212, v212, v213
	v_mov_b32_e32 v213, v212
	s_nop 1
	v_permlane16_swap_b32_e32 v213, v212
	s_waitcnt lgkmcnt(0)
	v_add_f32_e32 v212, v212, v213
	v_mov_b32_e32 v213, v212
	s_nop 1
	v_permlane32_swap_b32_e32 v213, v212
	s_and_saveexec_b64 s[8:9], s[6:7]
	s_cbranch_execz .LBB0_1204
	s_lshl_b32 s11, s83, 11
	s_add_i32 s11, s45, s11
	v_lshl_add_u32 v214, v219, 5, s11
	s_waitcnt lgkmcnt(0)
	v_add_f32_e32 v212, v212, v213
	v_mov_b32_e32 v213, v223
	ds_write_b64 v214, v[212:213] offset:1536
.LBB0_1204:
	s_or_b64 exec, exec, s[8:9]
	v_mul_f32_e32 v212, v127, v127
	s_waitcnt lgkmcnt(0)
	v_mul_f32_e32 v213, v129, v129
	v_fmac_f32_e32 v212, v126, v126
	v_fmac_f32_e32 v213, v128, v128
	v_add_f32_e32 v212, v212, v213
	v_mul_f32_e32 v213, v119, v119
	v_mul_f32_e32 v214, v121, v121
	v_fmac_f32_e32 v213, v118, v118
	v_fmac_f32_e32 v214, v120, v120
	v_add_f32_e32 v213, v213, v214
	v_add_f32_e32 v212, v212, v213
	v_mul_f32_e32 v213, v123, v123
	v_mul_f32_e32 v214, v125, v125
	v_fmac_f32_e32 v213, v122, v122
	v_fmac_f32_e32 v214, v124, v124
	v_add_f32_e32 v213, v213, v214
	v_add_f32_e32 v212, v212, v213
	v_mul_f32_e32 v213, v115, v115
	v_mul_f32_e32 v214, v117, v117
	v_fmac_f32_e32 v213, v114, v114
	v_fmac_f32_e32 v214, v116, v116
	v_add_f32_e32 v213, v213, v214
	v_add_f32_e32 v212, v212, v213
	v_mov_b32_e32 v213, v212
	s_nop 1
	v_permlane16_swap_b32_e32 v213, v212
	s_waitcnt lgkmcnt(0)
	v_add_f32_e32 v212, v212, v213
	v_mov_b32_e32 v213, v212
	s_nop 1
	v_permlane32_swap_b32_e32 v213, v212
	s_and_saveexec_b64 s[8:9], s[6:7]
	s_cbranch_execz .LBB0_1206
	s_lshl_b32 s11, s83, 11
	s_add_i32 s11, s45, s11
	v_lshl_add_u32 v214, v219, 5, s11
	s_waitcnt lgkmcnt(0)
	v_add_f32_e32 v212, v212, v213
	v_mov_b32_e32 v213, v223
	ds_write_b64 v214, v[212:213] offset:4096
.LBB0_1206:
	s_or_b64 exec, exec, s[8:9]
	v_mul_f32_e32 v212, v99, v99
	s_waitcnt lgkmcnt(0)
	v_mul_f32_e32 v213, v101, v101
	v_fmac_f32_e32 v212, v98, v98
	v_fmac_f32_e32 v213, v100, v100
	v_add_f32_e32 v212, v212, v213
	v_mul_f32_e32 v213, v91, v91
	v_mul_f32_e32 v214, v93, v93
	v_fmac_f32_e32 v213, v90, v90
	v_fmac_f32_e32 v214, v92, v92
	v_add_f32_e32 v213, v213, v214
	v_add_f32_e32 v212, v212, v213
	v_mul_f32_e32 v213, v71, v71
	v_mul_f32_e32 v214, v73, v73
	v_fmac_f32_e32 v213, v70, v70
	v_fmac_f32_e32 v214, v72, v72
	v_add_f32_e32 v213, v213, v214
	v_add_f32_e32 v212, v212, v213
	v_mul_f32_e32 v213, v63, v63
	v_mul_f32_e32 v214, v65, v65
	v_fmac_f32_e32 v213, v62, v62
	v_fmac_f32_e32 v214, v64, v64
	v_add_f32_e32 v213, v213, v214
	v_add_f32_e32 v212, v212, v213
	v_mov_b32_e32 v213, v212
	s_nop 1
	v_permlane16_swap_b32_e32 v213, v212
	s_waitcnt lgkmcnt(0)
	v_add_f32_e32 v212, v212, v213
	v_mov_b32_e32 v213, v212
	s_nop 1
	v_permlane32_swap_b32_e32 v213, v212
	s_and_saveexec_b64 s[8:9], s[6:7]
	s_cbranch_execz .LBB0_1208
	s_lshl_b32 s11, s83, 11
	s_add_i32 s11, s45, s11
	v_lshl_add_u32 v214, v219, 5, s11
	s_waitcnt lgkmcnt(0)
	v_add_f32_e32 v212, v212, v213
	v_mov_b32_e32 v213, v223
	ds_write_b64 v214, v[212:213] offset:4608
.LBB0_1208:
	s_or_b64 exec, exec, s[8:9]
	v_mul_f32_e32 v212, v47, v47
	s_waitcnt lgkmcnt(0)
	v_mul_f32_e32 v213, v49, v49
	v_fmac_f32_e32 v212, v46, v46
	v_fmac_f32_e32 v213, v48, v48
	v_add_f32_e32 v212, v212, v213
	v_mul_f32_e32 v213, v39, v39
	v_mul_f32_e32 v214, v41, v41
	v_fmac_f32_e32 v213, v38, v38
	v_fmac_f32_e32 v214, v40, v40
	v_add_f32_e32 v213, v213, v214
	v_add_f32_e32 v212, v212, v213
	v_mul_f32_e32 v213, v23, v23
	v_mul_f32_e32 v214, v25, v25
	v_fmac_f32_e32 v213, v22, v22
	v_fmac_f32_e32 v214, v24, v24
	v_add_f32_e32 v213, v213, v214
	v_add_f32_e32 v212, v212, v213
	v_mul_f32_e32 v213, v19, v19
	v_mul_f32_e32 v214, v21, v21
	v_fmac_f32_e32 v213, v18, v18
	v_fmac_f32_e32 v214, v20, v20
	v_add_f32_e32 v213, v213, v214
	v_add_f32_e32 v212, v212, v213
	v_mov_b32_e32 v213, v212
	s_nop 1
	v_permlane16_swap_b32_e32 v213, v212
	s_waitcnt lgkmcnt(0)
	v_add_f32_e32 v212, v212, v213
	v_mov_b32_e32 v213, v212
	s_nop 1
	v_permlane32_swap_b32_e32 v213, v212
	s_and_saveexec_b64 s[8:9], s[6:7]
	s_cbranch_execz .LBB0_1210
	s_lshl_b32 s11, s83, 11
	s_add_i32 s11, s45, s11
	v_lshl_add_u32 v214, v219, 5, s11
	s_waitcnt lgkmcnt(0)
	v_add_f32_e32 v212, v212, v213
	v_mov_b32_e32 v213, v223
	ds_write_b64 v214, v[212:213] offset:5120
.LBB0_1210:
	s_or_b64 exec, exec, s[8:9]
	v_mul_f32_e32 v212, v15, v15
	s_waitcnt lgkmcnt(0)
	v_mul_f32_e32 v213, v17, v17
	v_fmac_f32_e32 v212, v14, v14
	v_fmac_f32_e32 v213, v16, v16
	v_add_f32_e32 v212, v212, v213
	v_mul_f32_e32 v213, v11, v11
	v_mul_f32_e32 v214, v13, v13
	v_fmac_f32_e32 v213, v10, v10
	v_fmac_f32_e32 v214, v12, v12
	v_add_f32_e32 v213, v213, v214
	v_add_f32_e32 v212, v212, v213
	v_mul_f32_e32 v213, v7, v7
	v_mul_f32_e32 v214, v9, v9
	v_fmac_f32_e32 v213, v6, v6
	v_fmac_f32_e32 v214, v8, v8
	v_add_f32_e32 v213, v213, v214
	v_add_f32_e32 v212, v212, v213
	v_mul_f32_e32 v213, v3, v3
	v_mul_f32_e32 v214, v5, v5
	v_fmac_f32_e32 v213, v2, v2
	v_fmac_f32_e32 v214, v4, v4
	v_add_f32_e32 v213, v213, v214
	v_add_f32_e32 v212, v212, v213
	v_mov_b32_e32 v213, v212
	s_nop 1
	v_permlane16_swap_b32_e32 v213, v212
	s_waitcnt lgkmcnt(0)
	v_add_f32_e32 v212, v212, v213
	v_mov_b32_e32 v213, v212
	s_nop 1
	v_permlane32_swap_b32_e32 v213, v212
	s_and_saveexec_b64 s[8:9], s[6:7]
	s_cbranch_execz .LBB0_1212
	s_lshl_b32 s11, s83, 11
	s_add_i32 s11, s45, s11
	v_lshl_add_u32 v214, v219, 5, s11
	s_waitcnt lgkmcnt(0)
	v_add_f32_e32 v212, v212, v213
	v_mov_b32_e32 v213, v223
	ds_write_b64 v214, v[212:213] offset:5632

.LBB0_1340:
	s_and_b64 vcc, exec, s[4:5]
	s_cbranch_vccnz .LBB0_1152
	v_lshl_add_u64 v[130:131], s[64:65], 0, v[222:223]
	v_add_co_u32_e32 v132, vcc, 0x6000, v130
	s_mov_b64 s[4:5], 0x6000
	s_nop 0
	v_addc_co_u32_e32 v133, vcc, 0, v131, vcc
	v_lshl_add_u64 v[134:135], v[130:131], 0, s[4:5]
	global_load_dwordx4 v[138:141], v[132:133], off
	global_load_dwordx4 v[142:145], v[134:135], off offset:16
	s_mov_b64 s[4:5], 0x8000
	v_lshl_add_u64 v[158:159], v[130:131], 0, s[4:5]
	v_add_co_u32_e32 v130, vcc, 0x8000, v130
	s_waitcnt vmcnt(1)
	v_pk_mul_f32 v[164:165], v[32:33], v[140:141]
	v_addc_co_u32_e32 v131, vcc, 0, v131, vcc
	global_load_dwordx4 v[154:157], v[130:131], off
	global_load_dwordx4 v[146:149], v[158:159], off offset:16
	s_nop 0
	global_load_dwordx4 v[130:133], v[134:135], off offset:528
	s_nop 0
	global_load_dwordx4 v[134:137], v[134:135], off offset:512
	s_nop 0
	global_load_dwordx4 v[150:153], v[158:159], off offset:528
	s_nop 0
	global_load_dwordx4 v[158:161], v[158:159], off offset:512
	v_pk_mul_f32 v[166:167], v[30:31], v[138:139]
	v_max_f32_e64 v164, |v164|, |v165|
	v_max_f32_e64 v166, |v166|, |v167|
	v_max3_f32 v168, v166, 0, v164
	s_waitcnt vmcnt(6)
	v_pk_mul_f32 v[164:165], v[28:29], v[144:145]
	v_pk_mul_f32 v[166:167], v[26:27], v[142:143]
	v_max_f32_e64 v164, |v164|, |v165|
	v_max_f32_e64 v166, |v166|, |v167|
	v_max3_f32 v168, v168, v166, v164
	s_waitcnt vmcnt(2)
	v_pk_mul_f32 v[164:165], v[44:45], v[136:137]
	v_pk_mul_f32 v[166:167], v[42:43], v[134:135]
	v_max_f32_e64 v164, |v164|, |v165|
	v_max_f32_e64 v166, |v166|, |v167|
	v_max3_f32 v168, v168, v166, v164
	v_pk_mul_f32 v[164:165], v[36:37], v[132:133]
	v_pk_mul_f32 v[166:167], v[34:35], v[130:131]
	v_max_f32_e64 v164, |v164|, |v165|
	v_max_f32_e64 v166, |v166|, |v167|
	v_max3_f32 v166, v168, v166, v164
	v_mul_f32_e32 v164, v31, v31
	v_mul_f32_e32 v165, v33, v33
	v_fmac_f32_e32 v164, v30, v30
	v_fmac_f32_e32 v165, v32, v32
	v_add_f32_e32 v164, v164, v165
	v_mul_f32_e32 v165, v27, v27
	v_mul_f32_e32 v167, v29, v29
	v_fmac_f32_e32 v165, v26, v26
	v_fmac_f32_e32 v167, v28, v28
	v_add_f32_e32 v165, v165, v167
	v_add_f32_e32 v164, v164, v165
	v_mul_f32_e32 v165, v43, v43
	v_mul_f32_e32 v167, v45, v45
	v_fmac_f32_e32 v165, v42, v42
	v_fmac_f32_e32 v167, v44, v44
	v_add_f32_e32 v165, v165, v167
	v_add_f32_e32 v164, v165, v164
	v_mul_f32_e32 v165, v35, v35
	v_mul_f32_e32 v167, v37, v37
	v_fmac_f32_e32 v165, v34, v34
	v_fmac_f32_e32 v167, v36, v36
	v_add_f32_e32 v165, v165, v167
	v_add_f32_e32 v164, v165, v164
	v_mov_b32_e32 v167, v166
	v_mov_b32_e32 v165, v164
	s_nop 1
	v_permlane16_swap_b32_e32 v167, v166
	v_permlane16_swap_b32_e32 v165, v164
	s_waitcnt lgkmcnt(1)
	v_max_f32_e32 v167, v167, v167
	s_waitcnt lgkmcnt(0)
	v_add_f32_e32 v164, v164, v165
	v_max_f32_e32 v166, v166, v167
	v_mov_b32_e32 v165, v164
	v_mov_b32_e32 v167, v166
	s_nop 1
	v_permlane32_swap_b32_e32 v165, v164
	v_permlane32_swap_b32_e32 v167, v166
	s_and_saveexec_b64 s[4:5], s[6:7]
	s_cbranch_execz .LBB0_1343
	s_lshl_b32 s16, s83, 11
	s_add_i32 s16, s45, s16
	s_waitcnt lgkmcnt(1)
	v_add_f32_e32 v164, v164, v165
	s_waitcnt lgkmcnt(0)
	v_max_f32_e32 v165, v167, v167
	v_max_f32_e32 v166, v166, v166
	v_lshl_add_u32 v168, v219, 5, s16
	v_max_f32_e32 v165, v166, v165
	ds_write_b64 v168, v[164:165]
.LBB0_1343:
	s_or_b64 exec, exec, s[4:5]
	s_waitcnt lgkmcnt(1)
	v_pk_mul_f32 v[164:165], v[56:57], v[140:141]
	s_waitcnt lgkmcnt(0)
	v_pk_mul_f32 v[166:167], v[54:55], v[138:139]
	v_max_f32_e64 v164, |v164|, |v165|
	v_max_f32_e64 v166, |v166|, |v167|
	v_max3_f32 v168, v166, 0, v164
	v_pk_mul_f32 v[164:165], v[52:53], v[144:145]
	v_pk_mul_f32 v[166:167], v[50:51], v[142:143]
	v_max_f32_e64 v164, |v164|, |v165|
	v_max_f32_e64 v166, |v166|, |v167|
	v_max3_f32 v168, v168, v166, v164
	v_pk_mul_f32 v[164:165], v[68:69], v[136:137]
	v_pk_mul_f32 v[166:167], v[66:67], v[134:135]
	v_max_f32_e64 v164, |v164|, |v165|
	v_max_f32_e64 v166, |v166|, |v167|
	v_max3_f32 v168, v168, v166, v164
	v_pk_mul_f32 v[164:165], v[60:61], v[132:133]
	v_pk_mul_f32 v[166:167], v[58:59], v[130:131]
	v_max_f32_e64 v164, |v164|, |v165|
	v_max_f32_e64 v166, |v166|, |v167|
	v_max3_f32 v166, v168, v166, v164
	v_mul_f32_e32 v164, v55, v55
	v_mul_f32_e32 v165, v57, v57
	v_fmac_f32_e32 v164, v54, v54
	v_fmac_f32_e32 v165, v56, v56
	v_add_f32_e32 v164, v164, v165
	v_mul_f32_e32 v165, v51, v51
	v_mul_f32_e32 v167, v53, v53
	v_fmac_f32_e32 v165, v50, v50
	v_fmac_f32_e32 v167, v52, v52
	v_add_f32_e32 v165, v165, v167
	v_add_f32_e32 v164, v164, v165
	v_mul_f32_e32 v165, v67, v67
	v_mul_f32_e32 v167, v69, v69
	v_fmac_f32_e32 v165, v66, v66
	v_fmac_f32_e32 v167, v68, v68
	v_add_f32_e32 v165, v165, v167
	v_add_f32_e32 v164, v165, v164
	v_mul_f32_e32 v165, v59, v59
	v_mul_f32_e32 v167, v61, v61
	v_fmac_f32_e32 v165, v58, v58
	v_fmac_f32_e32 v167, v60, v60
	v_add_f32_e32 v165, v165, v167
	v_add_f32_e32 v164, v165, v164
	v_mov_b32_e32 v167, v166
	v_mov_b32_e32 v165, v164
	s_nop 1
	v_permlane16_swap_b32_e32 v167, v166
	v_permlane16_swap_b32_e32 v165, v164
	s_waitcnt lgkmcnt(1)
	v_max_f32_e32 v167, v167, v167
	s_waitcnt lgkmcnt(0)
	v_add_f32_e32 v164, v164, v165
	v_max_f32_e32 v166, v166, v167
	v_mov_b32_e32 v165, v164
	v_mov_b32_e32 v167, v166
	s_nop 1
	v_permlane32_swap_b32_e32 v165, v164
	v_permlane32_swap_b32_e32 v167, v166
	s_and_saveexec_b64 s[4:5], s[6:7]
	s_cbranch_execz .LBB0_1345
	s_lshl_b32 s16, s83, 11
	s_add_i32 s16, s45, s16
	s_waitcnt lgkmcnt(1)
	v_add_f32_e32 v164, v164, v165
	s_waitcnt lgkmcnt(0)
	v_max_f32_e32 v165, v167, v167
	v_max_f32_e32 v166, v166, v166
	v_lshl_add_u32 v168, v219, 5, s16
	v_max_f32_e32 v165, v166, v165
	ds_write_b64 v168, v[164:165] offset:512
.LBB0_1345:
	s_or_b64 exec, exec, s[4:5]
	s_waitcnt lgkmcnt(1)
	v_pk_mul_f32 v[164:165], v[80:81], v[140:141]
	s_waitcnt lgkmcnt(0)
	v_pk_mul_f32 v[166:167], v[78:79], v[138:139]
	v_max_f32_e64 v164, |v164|, |v165|
	v_max_f32_e64 v166, |v166|, |v167|
	v_max3_f32 v168, v166, 0, v164
	v_pk_mul_f32 v[164:165], v[76:77], v[144:145]
	v_pk_mul_f32 v[166:167], v[74:75], v[142:143]
	v_max_f32_e64 v164, |v164|, |v165|
	v_max_f32_e64 v166, |v166|, |v167|
	v_max3_f32 v168, v168, v166, v164
	v_pk_mul_f32 v[164:165], v[88:89], v[136:137]
	v_pk_mul_f32 v[166:167], v[86:87], v[134:135]
	v_max_f32_e64 v164, |v164|, |v165|
	v_max_f32_e64 v166, |v166|, |v167|
	v_max3_f32 v168, v168, v166, v164
	v_pk_mul_f32 v[164:165], v[84:85], v[132:133]
	v_pk_mul_f32 v[166:167], v[82:83], v[130:131]
	v_max_f32_e64 v164, |v164|, |v165|
	v_max_f32_e64 v166, |v166|, |v167|
	v_max3_f32 v166, v168, v166, v164
	v_mul_f32_e32 v164, v79, v79
	v_mul_f32_e32 v165, v81, v81
	v_fmac_f32_e32 v164, v78, v78
	v_fmac_f32_e32 v165, v80, v80
	v_add_f32_e32 v164, v164, v165
	v_mul_f32_e32 v165, v75, v75
	v_mul_f32_e32 v167, v77, v77
	v_fmac_f32_e32 v165, v74, v74
	v_fmac_f32_e32 v167, v76, v76
	v_add_f32_e32 v165, v165, v167
	v_add_f32_e32 v164, v164, v165
	v_mul_f32_e32 v165, v87, v87
	v_mul_f32_e32 v167, v89, v89
	v_fmac_f32_e32 v165, v86, v86
	v_fmac_f32_e32 v167, v88, v88
	v_add_f32_e32 v165, v165, v167
	v_add_f32_e32 v164, v165, v164
	v_mul_f32_e32 v165, v83, v83
	v_mul_f32_e32 v167, v85, v85
	v_fmac_f32_e32 v165, v82, v82
	v_fmac_f32_e32 v167, v84, v84
	v_add_f32_e32 v165, v165, v167
	v_add_f32_e32 v164, v165, v164
	v_mov_b32_e32 v167, v166
	v_mov_b32_e32 v165, v164
	s_nop 1
	v_permlane16_swap_b32_e32 v167, v166
	v_permlane16_swap_b32_e32 v165, v164
	s_waitcnt lgkmcnt(1)
	v_max_f32_e32 v167, v167, v167
	s_waitcnt lgkmcnt(0)
	v_add_f32_e32 v164, v164, v165
	v_max_f32_e32 v166, v166, v167
	v_mov_b32_e32 v165, v164
	v_mov_b32_e32 v167, v166
	s_nop 1
	v_permlane32_swap_b32_e32 v165, v164
	v_permlane32_swap_b32_e32 v167, v166
	s_and_saveexec_b64 s[4:5], s[6:7]
	s_cbranch_execz .LBB0_1347
	s_lshl_b32 s16, s83, 11
	s_add_i32 s16, s45, s16
	s_waitcnt lgkmcnt(1)
	v_add_f32_e32 v164, v164, v165
	s_waitcnt lgkmcnt(0)
	v_max_f32_e32 v165, v167, v167
	v_max_f32_e32 v166, v166, v166
	v_lshl_add_u32 v168, v219, 5, s16
	v_max_f32_e32 v165, v166, v165
	ds_write_b64 v168, v[164:165] offset:1024
.LBB0_1347:
	s_or_b64 exec, exec, s[4:5]
	s_waitcnt lgkmcnt(1)
	v_pk_mul_f32 v[164:165], v[104:105], v[140:141]
	s_waitcnt lgkmcnt(0)
	v_pk_mul_f32 v[166:167], v[102:103], v[138:139]
	v_max_f32_e64 v164, |v164|, |v165|
	v_max_f32_e64 v166, |v166|, |v167|
	v_max3_f32 v168, v166, 0, v164
	v_pk_mul_f32 v[164:165], v[96:97], v[144:145]
	v_pk_mul_f32 v[166:167], v[94:95], v[142:143]
	v_max_f32_e64 v164, |v164|, |v165|
	v_max_f32_e64 v166, |v166|, |v167|
	v_max3_f32 v168, v168, v166, v164
	v_pk_mul_f32 v[164:165], v[112:113], v[136:137]
	v_pk_mul_f32 v[166:167], v[110:111], v[134:135]
	v_max_f32_e64 v164, |v164|, |v165|
	v_max_f32_e64 v166, |v166|, |v167|
	v_max3_f32 v168, v168, v166, v164
	v_pk_mul_f32 v[164:165], v[108:109], v[132:133]
	v_pk_mul_f32 v[166:167], v[106:107], v[130:131]
	v_max_f32_e64 v164, |v164|, |v165|
	v_max_f32_e64 v166, |v166|, |v167|
	v_max3_f32 v166, v168, v166, v164
	v_mul_f32_e32 v164, v103, v103
	v_mul_f32_e32 v165, v105, v105
	v_fmac_f32_e32 v164, v102, v102
	v_fmac_f32_e32 v165, v104, v104
	v_add_f32_e32 v164, v164, v165
	v_mul_f32_e32 v165, v95, v95
	v_mul_f32_e32 v167, v97, v97
	v_fmac_f32_e32 v165, v94, v94
	v_fmac_f32_e32 v167, v96, v96
	v_add_f32_e32 v165, v165, v167
	v_add_f32_e32 v164, v164, v165
	v_mul_f32_e32 v165, v111, v111
	v_mul_f32_e32 v167, v113, v113
	v_fmac_f32_e32 v165, v110, v110
	v_fmac_f32_e32 v167, v112, v112
	v_add_f32_e32 v165, v165, v167
	v_add_f32_e32 v164, v165, v164
	v_mul_f32_e32 v165, v107, v107
	v_mul_f32_e32 v167, v109, v109
	v_fmac_f32_e32 v165, v106, v106
	v_fmac_f32_e32 v167, v108, v108
	v_add_f32_e32 v165, v165, v167
	v_add_f32_e32 v164, v165, v164
	v_mov_b32_e32 v167, v166
	v_mov_b32_e32 v165, v164
	s_nop 1
	v_permlane16_swap_b32_e32 v167, v166
	v_permlane16_swap_b32_e32 v165, v164
	s_waitcnt lgkmcnt(1)
	v_max_f32_e32 v167, v167, v167
	s_waitcnt lgkmcnt(0)
	v_add_f32_e32 v164, v164, v165
	v_max_f32_e32 v166, v166, v167
	v_mov_b32_e32 v165, v164
	v_mov_b32_e32 v167, v166
	s_nop 1
	v_permlane32_swap_b32_e32 v165, v164
	v_permlane32_swap_b32_e32 v167, v166
	s_and_saveexec_b64 s[4:5], s[6:7]
	s_cbranch_execz .LBB0_1349
	s_lshl_b32 s16, s83, 11
	s_add_i32 s16, s45, s16
	s_waitcnt lgkmcnt(1)
	v_add_f32_e32 v164, v164, v165
	s_waitcnt lgkmcnt(0)
	v_max_f32_e32 v165, v167, v167
	v_max_f32_e32 v166, v166, v166
	v_lshl_add_u32 v168, v219, 5, s16
	v_max_f32_e32 v165, v166, v165
	ds_write_b64 v168, v[164:165] offset:1536
.LBB0_1349:
	s_or_b64 exec, exec, s[4:5]
	s_waitcnt lgkmcnt(1)
	v_pk_mul_f32 v[164:165], v[128:129], v[140:141]
	s_waitcnt lgkmcnt(0)
	v_pk_mul_f32 v[166:167], v[126:127], v[138:139]
	v_max_f32_e64 v164, |v164|, |v165|
	v_max_f32_e64 v166, |v166|, |v167|
	v_max3_f32 v168, v166, 0, v164
	v_pk_mul_f32 v[164:165], v[120:121], v[144:145]
	v_pk_mul_f32 v[166:167], v[118:119], v[142:143]
	v_max_f32_e64 v164, |v164|, |v165|
	v_max_f32_e64 v166, |v166|, |v167|
	v_max3_f32 v168, v168, v166, v164
	v_pk_mul_f32 v[164:165], v[124:125], v[136:137]
	v_pk_mul_f32 v[166:167], v[122:123], v[134:135]
	v_max_f32_e64 v164, |v164|, |v165|
	v_max_f32_e64 v166, |v166|, |v167|
	v_max3_f32 v168, v168, v166, v164
	v_pk_mul_f32 v[164:165], v[116:117], v[132:133]
	v_pk_mul_f32 v[166:167], v[114:115], v[130:131]
	v_max_f32_e64 v164, |v164|, |v165|
	v_max_f32_e64 v166, |v166|, |v167|
	v_max3_f32 v166, v168, v166, v164
	v_mul_f32_e32 v164, v127, v127
	v_mul_f32_e32 v165, v129, v129
	v_fmac_f32_e32 v164, v126, v126
	v_fmac_f32_e32 v165, v128, v128
	v_add_f32_e32 v164, v164, v165
	v_mul_f32_e32 v165, v119, v119
	v_mul_f32_e32 v167, v121, v121
	v_fmac_f32_e32 v165, v118, v118
	v_fmac_f32_e32 v167, v120, v120
	v_add_f32_e32 v165, v165, v167
	v_add_f32_e32 v164, v164, v165
	v_mul_f32_e32 v165, v123, v123
	v_mul_f32_e32 v167, v125, v125
	v_fmac_f32_e32 v165, v122, v122
	v_fmac_f32_e32 v167, v124, v124
	v_add_f32_e32 v165, v165, v167
	v_add_f32_e32 v164, v165, v164
	v_mul_f32_e32 v165, v115, v115
	v_mul_f32_e32 v167, v117, v117
	v_fmac_f32_e32 v165, v114, v114
	v_fmac_f32_e32 v167, v116, v116
	v_add_f32_e32 v165, v165, v167
	v_add_f32_e32 v164, v165, v164
	v_mov_b32_e32 v167, v166
	v_mov_b32_e32 v165, v164
	s_nop 1
	v_permlane16_swap_b32_e32 v167, v166
	v_permlane16_swap_b32_e32 v165, v164
	s_waitcnt lgkmcnt(1)
	v_max_f32_e32 v167, v167, v167
	s_waitcnt lgkmcnt(0)
	v_add_f32_e32 v164, v164, v165
	v_max_f32_e32 v166, v166, v167
	v_mov_b32_e32 v165, v164
	v_mov_b32_e32 v167, v166
	s_nop 1
	v_permlane32_swap_b32_e32 v165, v164
	v_permlane32_swap_b32_e32 v167, v166
	s_and_saveexec_b64 s[4:5], s[6:7]
	s_cbranch_execz .LBB0_1351
	s_lshl_b32 s16, s83, 11
	s_add_i32 s16, s45, s16
	s_waitcnt lgkmcnt(1)
	v_add_f32_e32 v164, v164, v165
	s_waitcnt lgkmcnt(0)
	v_max_f32_e32 v165, v167, v167
	v_max_f32_e32 v166, v166, v166
	v_lshl_add_u32 v168, v219, 5, s16
	v_max_f32_e32 v165, v166, v165
	ds_write_b64 v168, v[164:165] offset:4096
.LBB0_1351:
	s_or_b64 exec, exec, s[4:5]
	s_waitcnt lgkmcnt(1)
	v_pk_mul_f32 v[164:165], v[100:101], v[140:141]
	s_waitcnt lgkmcnt(0)
	v_pk_mul_f32 v[166:167], v[98:99], v[138:139]
	v_max_f32_e64 v164, |v164|, |v165|
	v_max_f32_e64 v166, |v166|, |v167|
	v_max3_f32 v168, v166, 0, v164
	v_pk_mul_f32 v[164:165], v[92:93], v[144:145]
	v_pk_mul_f32 v[166:167], v[90:91], v[142:143]
	v_max_f32_e64 v164, |v164|, |v165|
	v_max_f32_e64 v166, |v166|, |v167|
	v_max3_f32 v168, v168, v166, v164
	v_pk_mul_f32 v[164:165], v[72:73], v[136:137]
	v_pk_mul_f32 v[166:167], v[70:71], v[134:135]
	v_max_f32_e64 v164, |v164|, |v165|
	v_max_f32_e64 v166, |v166|, |v167|
	v_max3_f32 v168, v168, v166, v164
	v_pk_mul_f32 v[164:165], v[64:65], v[132:133]
	v_pk_mul_f32 v[166:167], v[62:63], v[130:131]
	v_max_f32_e64 v164, |v164|, |v165|
	v_max_f32_e64 v166, |v166|, |v167|
	v_max3_f32 v166, v168, v166, v164
	v_mul_f32_e32 v164, v99, v99
	v_mul_f32_e32 v165, v101, v101
	v_fmac_f32_e32 v164, v98, v98
	v_fmac_f32_e32 v165, v100, v100
	v_add_f32_e32 v164, v164, v165
	v_mul_f32_e32 v165, v91, v91
	v_mul_f32_e32 v167, v93, v93
	v_fmac_f32_e32 v165, v90, v90
	v_fmac_f32_e32 v167, v92, v92
	v_add_f32_e32 v165, v165, v167
	v_add_f32_e32 v164, v164, v165
	v_mul_f32_e32 v165, v71, v71
	v_mul_f32_e32 v167, v73, v73
	v_fmac_f32_e32 v165, v70, v70
	v_fmac_f32_e32 v167, v72, v72
	v_add_f32_e32 v165, v165, v167
	v_add_f32_e32 v164, v165, v164
	v_mul_f32_e32 v165, v63, v63
	v_mul_f32_e32 v167, v65, v65
	v_fmac_f32_e32 v165, v62, v62
	v_fmac_f32_e32 v167, v64, v64
	v_add_f32_e32 v165, v165, v167
	v_add_f32_e32 v164, v165, v164
	v_mov_b32_e32 v167, v166
	v_mov_b32_e32 v165, v164
	s_nop 1
	v_permlane16_swap_b32_e32 v167, v166
	v_permlane16_swap_b32_e32 v165, v164
	s_waitcnt lgkmcnt(1)
	v_max_f32_e32 v167, v167, v167
	s_waitcnt lgkmcnt(0)
	v_add_f32_e32 v164, v164, v165
	v_max_f32_e32 v166, v166, v167
	v_mov_b32_e32 v165, v164
	v_mov_b32_e32 v167, v166
	s_nop 1
	v_permlane32_swap_b32_e32 v165, v164
	v_permlane32_swap_b32_e32 v167, v166
	s_and_saveexec_b64 s[4:5], s[6:7]
	s_cbranch_execz .LBB0_1353
	s_lshl_b32 s16, s83, 11
	s_add_i32 s16, s45, s16
	s_waitcnt lgkmcnt(1)
	v_add_f32_e32 v164, v164, v165
	s_waitcnt lgkmcnt(0)
	v_max_f32_e32 v165, v167, v167
	v_max_f32_e32 v166, v166, v166
	v_lshl_add_u32 v168, v219, 5, s16
	v_max_f32_e32 v165, v166, v165
	ds_write_b64 v168, v[164:165] offset:4608
.LBB0_1353:
	s_or_b64 exec, exec, s[4:5]
	s_waitcnt lgkmcnt(1)
	v_pk_mul_f32 v[164:165], v[48:49], v[140:141]
	s_waitcnt lgkmcnt(0)
	v_pk_mul_f32 v[166:167], v[46:47], v[138:139]
	v_max_f32_e64 v164, |v164|, |v165|
	v_max_f32_e64 v166, |v166|, |v167|
	v_max3_f32 v168, v166, 0, v164
	v_pk_mul_f32 v[164:165], v[40:41], v[144:145]
	v_pk_mul_f32 v[166:167], v[38:39], v[142:143]
	v_max_f32_e64 v164, |v164|, |v165|
	v_max_f32_e64 v166, |v166|, |v167|
	v_max3_f32 v168, v168, v166, v164
	v_pk_mul_f32 v[164:165], v[24:25], v[136:137]
	v_pk_mul_f32 v[166:167], v[22:23], v[134:135]
	v_max_f32_e64 v164, |v164|, |v165|
	v_max_f32_e64 v166, |v166|, |v167|
	v_max3_f32 v168, v168, v166, v164
	v_pk_mul_f32 v[164:165], v[20:21], v[132:133]
	v_pk_mul_f32 v[166:167], v[18:19], v[130:131]
	v_max_f32_e64 v164, |v164|, |v165|
	v_max_f32_e64 v166, |v166|, |v167|
	v_max3_f32 v166, v168, v166, v164
	v_mul_f32_e32 v164, v47, v47
	v_mul_f32_e32 v165, v49, v49
	v_fmac_f32_e32 v164, v46, v46
	v_fmac_f32_e32 v165, v48, v48
	v_add_f32_e32 v164, v164, v165
	v_mul_f32_e32 v165, v39, v39
	v_mul_f32_e32 v167, v41, v41
	v_fmac_f32_e32 v165, v38, v38
	v_fmac_f32_e32 v167, v40, v40
	v_add_f32_e32 v165, v165, v167
	v_add_f32_e32 v164, v164, v165
	v_mul_f32_e32 v165, v23, v23
	v_mul_f32_e32 v167, v25, v25
	v_fmac_f32_e32 v165, v22, v22
	v_fmac_f32_e32 v167, v24, v24
	v_add_f32_e32 v165, v165, v167
	v_add_f32_e32 v164, v165, v164
	v_mul_f32_e32 v165, v19, v19
	v_mul_f32_e32 v167, v21, v21
	v_fmac_f32_e32 v165, v18, v18
	v_fmac_f32_e32 v167, v20, v20
	v_add_f32_e32 v165, v165, v167
	v_add_f32_e32 v164, v165, v164
	v_mov_b32_e32 v167, v166
	v_mov_b32_e32 v165, v164
	s_nop 1
	v_permlane16_swap_b32_e32 v167, v166
	v_permlane16_swap_b32_e32 v165, v164
	s_waitcnt lgkmcnt(1)
	v_max_f32_e32 v167, v167, v167
	s_waitcnt lgkmcnt(0)
	v_add_f32_e32 v164, v164, v165
	v_max_f32_e32 v166, v166, v167
	v_mov_b32_e32 v165, v164
	v_mov_b32_e32 v167, v166
	s_nop 1
	v_permlane32_swap_b32_e32 v165, v164
	v_permlane32_swap_b32_e32 v167, v166
	s_and_saveexec_b64 s[4:5], s[6:7]
	s_cbranch_execz .LBB0_1355
	s_lshl_b32 s16, s83, 11
	s_add_i32 s16, s45, s16
	s_waitcnt lgkmcnt(1)
	v_add_f32_e32 v164, v164, v165
	s_waitcnt lgkmcnt(0)
	v_max_f32_e32 v165, v167, v167
	v_max_f32_e32 v166, v166, v166
	v_lshl_add_u32 v168, v219, 5, s16
	v_max_f32_e32 v165, v166, v165
	ds_write_b64 v168, v[164:165] offset:5120
.LBB0_1355:
	s_or_b64 exec, exec, s[4:5]
	s_waitcnt lgkmcnt(1)
	v_pk_mul_f32 v[164:165], v[16:17], v[140:141]
	s_waitcnt lgkmcnt(0)
	v_pk_mul_f32 v[166:167], v[14:15], v[138:139]
	v_max_f32_e64 v164, |v164|, |v165|
	v_max_f32_e64 v166, |v166|, |v167|
	v_max3_f32 v168, v166, 0, v164
	v_pk_mul_f32 v[164:165], v[12:13], v[144:145]
	v_pk_mul_f32 v[166:167], v[10:11], v[142:143]
	v_max_f32_e64 v164, |v164|, |v165|
	v_max_f32_e64 v166, |v166|, |v167|
	v_max3_f32 v168, v168, v166, v164
	v_pk_mul_f32 v[164:165], v[8:9], v[136:137]
	v_pk_mul_f32 v[166:167], v[6:7], v[134:135]
	v_max_f32_e64 v164, |v164|, |v165|
	v_max_f32_e64 v166, |v166|, |v167|
	v_max3_f32 v168, v168, v166, v164
	v_pk_mul_f32 v[164:165], v[4:5], v[132:133]
	v_pk_mul_f32 v[166:167], v[2:3], v[130:131]
	v_max_f32_e64 v164, |v164|, |v165|
	v_max_f32_e64 v166, |v166|, |v167|
	v_max3_f32 v166, v168, v166, v164
	v_mul_f32_e32 v164, v15, v15
	v_mul_f32_e32 v165, v17, v17
	v_fmac_f32_e32 v164, v14, v14
	v_fmac_f32_e32 v165, v16, v16
	v_add_f32_e32 v164, v164, v165
	v_mul_f32_e32 v165, v11, v11
	v_mul_f32_e32 v167, v13, v13
	v_fmac_f32_e32 v165, v10, v10
	v_fmac_f32_e32 v167, v12, v12
	v_add_f32_e32 v165, v165, v167
	v_add_f32_e32 v164, v164, v165
	v_mul_f32_e32 v165, v7, v7
	v_mul_f32_e32 v167, v9, v9
	v_fmac_f32_e32 v165, v6, v6
	v_fmac_f32_e32 v167, v8, v8
	v_add_f32_e32 v165, v165, v167
	v_add_f32_e32 v164, v165, v164
	v_mul_f32_e32 v165, v3, v3
	v_mul_f32_e32 v167, v5, v5
	v_fmac_f32_e32 v165, v2, v2
	v_fmac_f32_e32 v167, v4, v4
	v_add_f32_e32 v165, v165, v167
	v_add_f32_e32 v164, v165, v164
	v_mov_b32_e32 v167, v166
	v_mov_b32_e32 v165, v164
	s_nop 1
	v_permlane16_swap_b32_e32 v167, v166
	v_permlane16_swap_b32_e32 v165, v164
	s_waitcnt lgkmcnt(1)
	v_max_f32_e32 v167, v167, v167
	s_waitcnt lgkmcnt(0)
	v_add_f32_e32 v164, v164, v165
	v_max_f32_e32 v166, v166, v167
	v_mov_b32_e32 v165, v164
	v_mov_b32_e32 v167, v166
	s_nop 1
	v_permlane32_swap_b32_e32 v165, v164
	v_permlane32_swap_b32_e32 v167, v166
	s_and_saveexec_b64 s[4:5], s[6:7]
	s_cbranch_execz .LBB0_1357
	s_lshl_b32 s6, s83, 11
	s_add_i32 s45, s45, s6
	s_waitcnt lgkmcnt(1)
	v_add_f32_e32 v164, v164, v165
	s_waitcnt lgkmcnt(0)
	v_max_f32_e32 v165, v167, v167
	v_max_f32_e32 v166, v166, v166
	v_lshl_add_u32 v168, v219, 5, s45
	v_max_f32_e32 v165, v166, v165
	ds_write_b64 v168, v[164:165] offset:5632
